# P1 static schedule: column tiles 2,3 (GLU epilogue) and 8,9 (v, cheapest epilogue) swapped so the workgroups that also run the weight-copy tail get the cheap epilogues
# baseline (speedup 1.0000x reference)
;     __device__ __forceinline__ bool next(int i, Unit& u) const { if (i >= count) return false; const int L = first + i; u.pm = L / nN; u.pn = L % nN; return true; }
;     __host__ __device__ bool next(int i, Unit& u) const {
;         const long L = (long)i * G + c; if (L >= nwg) return false;
;         int wgid = (int)L; { const int q = nwg / NXCD, r = nwg % NXCD, xcd = wgid % NXCD, off = wgid / NXCD; wgid = (xcd < r ? xcd * (q + 1) : r * (q + 1) + (xcd - r) * q) + off; }
;         const int nig = WGM * nN, gid = wgid / nig, fm = gid * WGM, gsz = (nM - fm) < WGM ? (nM - fm) : WGM;
;         u.pm = fm + ((wgid % nig) % gsz); u.pn = (wgid % nig) / gsz; return true;
; __global__ void __launch_bounds__(NWAVES * 64, 2) fwd_kernel(Args args) {
;     ...
;         { pg8::Gemm g{XN, Win_t, M, INW, D}; pg8::StaticOrder S; S.init(M, INW, G, bx);
;           pg8::EpiIn E{Ub, MIX, Kb, Vb, ropec, ropes, kms};
;           pg8::gemm_phase<pg8::EpiIn, pg8::StaticOrder, true, true>(lds + RING_OFF, g, S, E); }
.LBB0_218:
	s_cmp_lt_i32 s76, 2
	s_cselect_b64 s[0:1], -1, 0
	s_add_u32 s18, s22, 0x7500000
	s_addc_u32 s19, s23, 0
	s_add_u32 s12, s22, 0x9500000
	s_addc_u32 s13, s23, 0
	s_add_u32 s16, s22, 0x6500000
	s_addc_u32 s17, s23, 0
	s_add_u32 s20, s22, 0x8500000
	s_addc_u32 s21, s23, 0
	s_add_u32 s2, s22, 0x10000
	v_writelane_b32 v254, s2, 25
	s_addc_u32 s2, s23, 0
	v_writelane_b32 v254, s2, 26
	s_and_b64 s[14:15], s[0:1], s[36:37]
	s_andn2_b64 vcc, exec, s[14:15]
	v_writelane_b32 v254, s70, 27
	s_nop 1
	v_writelane_b32 v254, s71, 28
	s_cbranch_vccnz .LBB0_453
	v_readfirstlane_b32 s2, v0
	s_lshr_b32 s3, s2, 6
	s_cmpk_lt_i32 s10, 0x280
	s_cselect_b64 s[0:1], -1, 0
	s_cmpk_gt_i32 s10, 0x27f
	s_cbranch_scc1 .LBB0_221
	s_ashr_i32 s4, s10, 31
	s_lshr_b32 s4, s4, 29
	s_add_i32 s4, s10, s4
	s_ashr_i32 s5, s4, 3
	s_and_b32 s4, s4, -8
	s_sub_i32 s4, s10, s4
	s_cmp_lt_i32 s4, 0
	s_movk_i32 s6, 0x51
	s_cselect_b32 s6, s6, 0x50
	s_mul_i32 s4, s4, s6
	s_add_i32 s4, s4, s5
	s_mul_hi_i32 s5, s4, 0x66666667
	s_lshr_b32 s6, s5, 31
	s_ashr_i32 s5, s5, 5
	s_add_i32 s5, s5, s6
	s_lshl_b32 s6, s5, 3
	s_mulk_i32 s5, 0x50
	s_sub_i32 s4, s4, s5
	s_bfe_i32 s5, s4, 0x80000
	s_bfe_u32 s5, s5, 0x3000c
	s_add_i32 s5, s4, s5
	s_bfe_i32 s7, s5, 0x80000
	s_and_b32 s5, s5, 0xf8
	s_sub_i32 s4, s4, s5
	s_sext_i32_i16 s7, s7
	s_sext_i32_i8 s4, s4
	s_add_i32 s60, s6, s4
	s_ashr_i32 s58, s7, 3
	s_add_i32 s98, s58, -2
	s_cmp_lt_u32 s98, 2
	s_cselect_b32 s99, 6, 0
	s_add_i32 s98, s58, -8
	s_cmp_lt_u32 s98, 2
	s_cselect_b32 s98, -6, 0
	s_add_i32 s58, s58, s99
	s_add_i32 s58, s58, s98

;     __device__ __forceinline__ bool next(int i, Unit& u) const { if (i >= count) return false; const int L = first + i; u.pm = L / nN; u.pn = L % nN; return true; }
;     __host__ __device__ bool next(int i, Unit& u) const {
;         const long L = (long)i * G + c; if (L >= nwg) return false;
;         int wgid = (int)L; { const int q = nwg / NXCD, r = nwg % NXCD, xcd = wgid % NXCD, off = wgid / NXCD; wgid = (xcd < r ? xcd * (q + 1) : r * (q + 1) + (xcd - r) * q) + off; }
;         const int nig = WGM * nN, gid = wgid / nig, fm = gid * WGM, gsz = (nM - fm) < WGM ? (nM - fm) : WGM;
;         u.pm = fm + ((wgid % nig) % gsz); u.pn = (wgid % nig) / gsz; return true;
;     }
.LBB0_227:
	s_add_i32 s67, s67, 1
	s_mul_i32 s1, s67, s31
	s_mul_hi_u32 s2, s67, s69
	s_add_i32 s2, s2, s1
	s_mul_i32 s1, s67, s69
	s_add_u32 s8, s1, s10
	s_addc_u32 s9, s2, s33
	v_cmp_gt_i64_e64 s[4:5], s[8:9], v[196:197]
	v_cmp_lt_i64_e64 s[2:3], s[8:9], v[194:195]
	s_and_b64 vcc, exec, s[4:5]
	s_cbranch_vccnz .LBB0_229
	s_ashr_i32 s0, s8, 31
	s_lshr_b32 s0, s0, 29
	s_add_i32 s0, s8, s0
	s_ashr_i32 s1, s0, 3
	s_and_b32 s0, s0, -8
	s_sub_i32 s0, s8, s0
	s_cmp_lt_i32 s0, 0
	s_movk_i32 s8, 0x51
	s_cselect_b32 s8, s8, 0x50
	s_mul_i32 s0, s0, s8
	s_add_i32 s0, s0, s1
	s_mul_hi_i32 s1, s0, 0x66666667
	s_lshr_b32 s8, s1, 31
	s_ashr_i32 s1, s1, 5
	s_add_i32 s1, s1, s8
	s_lshl_b32 s8, s1, 3
	s_sub_i32 s9, 64, s8
	s_min_i32 s9, s9, 8
	s_abs_i32 s11, s9
	v_cvt_f32_u32_e32 v2, s11
	s_sub_i32 s25, 0, s11
	s_mulk_i32 s1, 0x50
	s_sub_i32 s1, s0, s1
	v_rcp_iflag_f32_e32 v2, v2
	s_abs_i32 s0, s1
	s_xor_b32 s24, s1, s9
	s_ashr_i32 s24, s24, 31
	v_mul_f32_e32 v2, 0x4f7ffffe, v2
	v_cvt_u32_f32_e32 v2, v2
	s_nop 0
	v_readfirstlane_b32 s26, v2
	s_mul_i32 s25, s25, s26
	s_mul_hi_u32 s25, s26, s25
	s_add_i32 s26, s26, s25
	s_mul_hi_u32 s25, s0, s26
	s_mul_i32 s26, s25, s11
	s_sub_i32 s0, s0, s26
	s_add_i32 s27, s25, 1
	s_sub_i32 s26, s0, s11
	s_cmp_ge_u32 s0, s11
	s_cselect_b32 s25, s27, s25
	s_cselect_b32 s0, s26, s0
	s_add_i32 s26, s25, 1
	s_cmp_ge_u32 s0, s11
	s_cselect_b32 s0, s26, s25
	s_xor_b32 s0, s0, s24
	s_sub_i32 s0, s0, s24
	s_mul_i32 s9, s0, s9
	s_sub_i32 s1, s1, s9
	s_add_i32 s52, s8, s1
	s_add_i32 s98, s0, -2
	s_cmp_lt_u32 s98, 2
	s_cselect_b32 s99, 6, 0
	s_add_i32 s98, s0, -8
	s_cmp_lt_u32 s98, 2
	s_cselect_b32 s98, -6, 0
	s_add_i32 s0, s0, s99
	s_add_i32 s0, s0, s98
